# phase 0 filter MLP: per-layer W1/W2 cache lines touched up front so the serialized weight loads hit the vector cache; on top of previous version
# speedup vs baseline: 1.0019x; 1.0019x over previous
; DI void phase_prologue(const Params& p, LAS unsigned char* lds) {
;     ...
;         for (int l = 0; l < DEPTH; ++l) {
;             float a1 = p.in[I_HYB1][l * 64 + j];
;             for (int e = 0; e < 33; ++e) a1 += zemb[rl * 36 + e] * p.in[I_HYW1][(l * 33 + e) * 64 + j];
;             h1[rl * 64 + j] = sinf(p.in[I_HYFREQ][(l * 2 + 0) * 64 + j] * a1);
;             __syncthreads();
;             float a2 = p.in[I_HYB2][l * 64 + j];
;             for (int e = 0; e < 64; ++e) a2 += h1[rl * 64 + e] * p.in[I_HYW2][(l * 64 + e) * 64 + j];
;             hid2[((size_t)l * S + i) * 64 + j] = sinf(p.in[I_HYFREQ][(l * 2 + 1) * 64 + j] * a2);
.LBB0_943:
	v_mul_u32_u24_e32 v60, 0x7c, v15
	v_mov_b32_e32 v61, 0
	v_lshl_add_u64 v[62:63], v[10:11], 0, v[60:61]
	global_load_dword v64, v[62:63], off
	v_lshl_add_u64 v[62:63], v[8:9], 0, v[60:61]
	global_load_dword v65, v[62:63], off
	v_add_u32_e32 v60, 0x2000, v60
	v_lshl_add_u64 v[62:63], v[8:9], 0, v[60:61]
	global_load_dword v66, v[62:63], off
	v_lshl_or_b32 v96, s8, 6, v15
	v_lshl_add_u64 v[12:13], v[96:97], 2, s[54:55]
	global_load_dword v21, v[12:13], off
	s_mov_b64 s[6:7], 0
	v_mov_b32_e32 v12, v17
